# v55 + P11 GEMM loop: leading half (wr==0) waits for its stage loads before BAR#2 (after its MMA block) instead of before BAR#1; lagging half unchanged
# baseline (speedup 1.0000x reference)
.LBB0_975:
	ds_read_b128 v[116:119], v185
	ds_read_b128 v[120:123], v185 offset:1024
	ds_read_b128 v[124:127], v185 offset:2048
	ds_read_b128 v[132:135], v185 offset:3072
	ds_read_b128 v[166:169], v186
	ds_read_b128 v[170:173], v186 offset:1024
	ds_read_b128 v[174:177], v186 offset:2048
	ds_read_b128 v[178:181], v186 offset:3072
	s_add_u32 s40, s38, 0xfff80080
	s_addc_u32 s41, s39, -1
	s_cmp_eq_u32 s59, 28
	s_cselect_b32 s43, s1, s41
	s_cselect_b32 s42, s3, s40
	s_cselect_b32 s41, s29, s58
	s_cselect_b32 s40, s31, s57
	v_lshl_add_u64 v[224:225], s[38:39], 0, v[156:157]
	s_add_i32 m0, s33, 0xc000
	ds_read_b128 v[192:195], v187
	ds_read_b128 v[196:199], v187 offset:1024
	ds_read_b128 v[200:203], v187 offset:2048
	ds_read_b128 v[204:207], v187 offset:3072
	ds_read_b128 v[208:211], v187 offset:4096
	ds_read_b128 v[212:215], v187 offset:5120
	ds_read_b128 v[216:219], v187 offset:6144
	ds_read_b128 v[220:223], v187 offset:7168
	global_load_lds_dwordx4 v[224:225], off
	v_lshl_add_u64 v[224:225], s[38:39], 0, v[158:159]
	s_add_i32 m0, s33, 0xe000
	s_nop 0
	global_load_lds_dwordx4 v[224:225], off
	s_cmp_lg_u32 s22, 0
	s_cbranch_scc1 .Lgw1_1
	s_waitcnt vmcnt(8)
.Lgw1_1:
	s_waitcnt lgkmcnt(0)
	s_barrier
	s_setprio 1
	s_waitcnt lgkmcnt(0)
	v_mfma_f32_16x16x32_bf16 v[136:139], v[116:119], v[192:195], v[136:139]
	v_mfma_f32_16x16x32_bf16 v[56:59], v[124:127], v[192:195], v[56:59]
	v_mfma_f32_16x16x32_bf16 v[112:115], v[116:119], v[200:203], v[112:115]
	v_mfma_f32_16x16x32_bf16 v[48:51], v[124:127], v[200:203], v[48:51]
	v_mfma_f32_16x16x32_bf16 v[104:107], v[116:119], v[208:211], v[104:107]
	v_mfma_f32_16x16x32_bf16 v[40:43], v[124:127], v[208:211], v[40:43]
	v_mfma_f32_16x16x32_bf16 v[100:103], v[116:119], v[216:219], v[100:103]
	v_mfma_f32_16x16x32_bf16 v[36:39], v[124:127], v[216:219], v[36:39]
	v_mfma_f32_16x16x32_bf16 v[136:139], v[120:123], v[196:199], v[136:139]
	v_mfma_f32_16x16x32_bf16 v[56:59], v[132:135], v[196:199], v[56:59]
	v_mfma_f32_16x16x32_bf16 v[112:115], v[120:123], v[204:207], v[112:115]
	v_mfma_f32_16x16x32_bf16 v[48:51], v[132:135], v[204:207], v[48:51]
	v_mfma_f32_16x16x32_bf16 v[104:107], v[120:123], v[212:215], v[104:107]
	v_mfma_f32_16x16x32_bf16 v[40:43], v[132:135], v[212:215], v[40:43]
	v_mfma_f32_16x16x32_bf16 v[100:103], v[120:123], v[220:223], v[100:103]
	v_mfma_f32_16x16x32_bf16 v[36:39], v[132:135], v[220:223], v[36:39]
	v_mfma_f32_16x16x32_bf16 v[140:143], v[166:169], v[192:195], v[140:143]
	v_mfma_f32_16x16x32_bf16 v[60:63], v[174:177], v[192:195], v[60:63]
	v_mfma_f32_16x16x32_bf16 v[128:131], v[166:169], v[200:203], v[128:131]
	v_mfma_f32_16x16x32_bf16 v[52:55], v[174:177], v[200:203], v[52:55]
	v_mfma_f32_16x16x32_bf16 v[108:111], v[166:169], v[208:211], v[108:111]
	v_mfma_f32_16x16x32_bf16 v[44:47], v[174:177], v[208:211], v[44:47]
	v_mfma_f32_16x16x32_bf16 v[96:99], v[166:169], v[216:219], v[96:99]
	v_mfma_f32_16x16x32_bf16 v[32:35], v[174:177], v[216:219], v[32:35]
	v_mfma_f32_16x16x32_bf16 v[140:143], v[170:173], v[196:199], v[140:143]
	v_mfma_f32_16x16x32_bf16 v[60:63], v[178:181], v[196:199], v[60:63]
	v_mfma_f32_16x16x32_bf16 v[128:131], v[170:173], v[204:207], v[128:131]
	v_mfma_f32_16x16x32_bf16 v[52:55], v[178:181], v[204:207], v[52:55]
	v_mfma_f32_16x16x32_bf16 v[108:111], v[170:173], v[212:215], v[108:111]
	v_mfma_f32_16x16x32_bf16 v[44:47], v[178:181], v[212:215], v[44:47]
	v_mfma_f32_16x16x32_bf16 v[96:99], v[170:173], v[220:223], v[96:99]
	v_mfma_f32_16x16x32_bf16 v[32:35], v[178:181], v[220:223], v[32:35]
	s_setprio 0
	s_cmp_eq_u32 s22, 0
	s_cbranch_scc1 .Lgw2_1
	s_waitcnt vmcnt(8)
.Lgw2_1:
	s_barrier
	s_add_i32 s60, s53, s93
	v_lshl_add_u64 v[224:225], s[40:41], 0, v[146:147]
	s_mov_b32 m0, s60
	ds_read_b128 v[192:195], v187 offset:16384
	ds_read_b128 v[196:199], v187 offset:17408
	ds_read_b128 v[200:203], v187 offset:18432
	ds_read_b128 v[204:207], v187 offset:19456
	ds_read_b128 v[208:211], v187 offset:20480
	ds_read_b128 v[212:215], v187 offset:21504
	ds_read_b128 v[216:219], v187 offset:22528
	ds_read_b128 v[220:223], v187 offset:23552
	global_load_lds_dwordx4 v[224:225], off
	s_add_i32 m0, s60, 0x2000
	s_add_u32 s60, s40, 0x80000
	v_lshl_add_u64 v[226:227], s[40:41], 0, v[150:151]
	s_addc_u32 s61, s41, 0
	s_add_i32 s62, s54, s93
	global_load_lds_dwordx4 v[226:227], off
	v_lshl_add_u64 v[228:229], s[60:61], 0, v[146:147]
	s_mov_b32 m0, s62
	v_lshl_add_u64 v[230:231], s[42:43], 0, v[148:149]
	global_load_lds_dwordx4 v[228:229], off
	v_lshl_add_u64 v[228:229], s[60:61], 0, v[150:151]
	s_add_i32 m0, s62, 0x2000
	s_nop 0
	global_load_lds_dwordx4 v[228:229], off
	v_lshl_add_u64 v[228:229], s[42:43], 0, v[144:145]
	s_mov_b32 m0, s33
	s_nop 0
	global_load_lds_dwordx4 v[228:229], off
	s_mov_b32 m0, s44
	s_nop 0
	global_load_lds_dwordx4 v[230:231], off
	s_cmp_lg_u32 s22, 0
	s_cbranch_scc1 .Lgw1_2
	s_waitcnt vmcnt(8)
.Lgw1_2:
	s_waitcnt lgkmcnt(0)
	s_barrier
	s_setprio 1
	s_waitcnt lgkmcnt(0)
	v_mfma_f32_16x16x32_bf16 v[88:91], v[116:119], v[192:195], v[88:91]
	v_mfma_f32_16x16x32_bf16 v[24:27], v[124:127], v[192:195], v[24:27]
	v_mfma_f32_16x16x32_bf16 v[80:83], v[116:119], v[200:203], v[80:83]
	v_mfma_f32_16x16x32_bf16 v[16:19], v[124:127], v[200:203], v[16:19]
	v_mfma_f32_16x16x32_bf16 v[72:75], v[116:119], v[208:211], v[72:75]
	v_mfma_f32_16x16x32_bf16 v[8:11], v[124:127], v[208:211], v[8:11]
	v_mfma_f32_16x16x32_bf16 v[68:71], v[116:119], v[216:219], v[68:71]
	v_mfma_f32_16x16x32_bf16 v[4:7], v[124:127], v[216:219], v[4:7]
	v_mfma_f32_16x16x32_bf16 v[88:91], v[120:123], v[196:199], v[88:91]
	v_mfma_f32_16x16x32_bf16 v[24:27], v[132:135], v[196:199], v[24:27]
	v_mfma_f32_16x16x32_bf16 v[80:83], v[120:123], v[204:207], v[80:83]
	v_mfma_f32_16x16x32_bf16 v[16:19], v[132:135], v[204:207], v[16:19]
	v_mfma_f32_16x16x32_bf16 v[72:75], v[120:123], v[212:215], v[72:75]
	v_mfma_f32_16x16x32_bf16 v[8:11], v[132:135], v[212:215], v[8:11]
	v_mfma_f32_16x16x32_bf16 v[68:71], v[120:123], v[220:223], v[68:71]
	v_mfma_f32_16x16x32_bf16 v[4:7], v[132:135], v[220:223], v[4:7]
	v_mfma_f32_16x16x32_bf16 v[92:95], v[166:169], v[192:195], v[92:95]
	v_mfma_f32_16x16x32_bf16 v[28:31], v[174:177], v[192:195], v[28:31]
	v_mfma_f32_16x16x32_bf16 v[84:87], v[166:169], v[200:203], v[84:87]
	v_mfma_f32_16x16x32_bf16 v[20:23], v[174:177], v[200:203], v[20:23]
	v_mfma_f32_16x16x32_bf16 v[76:79], v[166:169], v[208:211], v[76:79]
	v_mfma_f32_16x16x32_bf16 v[12:15], v[174:177], v[208:211], v[12:15]
	v_mfma_f32_16x16x32_bf16 v[64:67], v[166:169], v[216:219], v[64:67]
	v_mfma_f32_16x16x32_bf16 v[0:3], v[174:177], v[216:219], v[0:3]
	v_mfma_f32_16x16x32_bf16 v[92:95], v[170:173], v[196:199], v[92:95]
	v_mfma_f32_16x16x32_bf16 v[28:31], v[178:181], v[196:199], v[28:31]
	v_mfma_f32_16x16x32_bf16 v[84:87], v[170:173], v[204:207], v[84:87]
	v_mfma_f32_16x16x32_bf16 v[20:23], v[178:181], v[204:207], v[20:23]
	v_mfma_f32_16x16x32_bf16 v[76:79], v[170:173], v[212:215], v[76:79]
	v_mfma_f32_16x16x32_bf16 v[12:15], v[178:181], v[212:215], v[12:15]
	v_mfma_f32_16x16x32_bf16 v[64:67], v[170:173], v[220:223], v[64:67]
	v_mfma_f32_16x16x32_bf16 v[0:3], v[178:181], v[220:223], v[0:3]
	s_setprio 0
	s_cmp_eq_u32 s22, 0
	s_cbranch_scc1 .Lgw2_2
	s_waitcnt vmcnt(8)
.Lgw2_2:
	s_barrier
	s_add_i32 s60, 0, 0x18000
	s_add_i32 s61, 0, 0x1c000
	v_add_u32_e32 v132, s60, v183
	v_add_u32_e32 v178, s61, v183
	ds_read_b128 v[116:119], v132
	ds_read_b128 v[120:123], v132 offset:1024
	ds_read_b128 v[124:127], v132 offset:2048
	ds_read_b128 v[132:135], v132 offset:3072
	ds_read_b128 v[166:169], v178
	ds_read_b128 v[170:173], v178 offset:1024
	ds_read_b128 v[174:177], v178 offset:2048
	ds_read_b128 v[178:181], v178 offset:3072
	s_add_u32 s42, s42, 0x80000
	s_addc_u32 s43, s43, 0
	s_mov_b32 m0, s45
	v_lshl_add_u64 v[232:233], s[42:43], 0, v[144:145]
	ds_read_b128 v[192:195], v187 offset:32768
	ds_read_b128 v[196:199], v187 offset:33792
	ds_read_b128 v[200:203], v187 offset:34816
	ds_read_b128 v[204:207], v187 offset:35840
	ds_read_b128 v[208:211], v187 offset:36864
	ds_read_b128 v[212:215], v187 offset:37888
	ds_read_b128 v[216:219], v187 offset:38912
	ds_read_b128 v[220:223], v187 offset:39936
	global_load_lds_dwordx4 v[232:233], off
	v_lshl_add_u64 v[232:233], s[42:43], 0, v[148:149]
	s_mov_b32 m0, s46
	s_nop 0
	global_load_lds_dwordx4 v[232:233], off
	s_cmp_lg_u32 s22, 0
	s_cbranch_scc1 .Lgw1_3
	s_waitcnt vmcnt(8)

.Lgw2_3:
	s_barrier
	s_add_i32 s42, s60, s93
	v_lshl_add_u64 v[224:225], v[224:225], 0, s[20:21]
	s_mov_b32 m0, s42
	ds_read_b128 v[192:195], v187 offset:49152
	ds_read_b128 v[196:199], v187 offset:50176
	ds_read_b128 v[200:203], v187 offset:51200
	ds_read_b128 v[204:207], v187 offset:52224
	ds_read_b128 v[208:211], v187 offset:53248
	ds_read_b128 v[212:215], v187 offset:54272
	ds_read_b128 v[216:219], v187 offset:55296
	ds_read_b128 v[220:223], v187 offset:56320
	global_load_lds_dwordx4 v[224:225], off
	s_add_i32 m0, s42, 0x2000
	s_add_u32 s40, s40, 0x80080
	v_lshl_add_u64 v[224:225], v[226:227], 0, s[20:21]
	s_addc_u32 s41, s41, 0
	s_add_i32 s42, s61, s93
	global_load_lds_dwordx4 v[224:225], off
	v_lshl_add_u64 v[224:225], s[40:41], 0, v[146:147]
	s_mov_b32 m0, s42
	s_nop 0
	global_load_lds_dwordx4 v[224:225], off
	v_lshl_add_u64 v[224:225], s[40:41], 0, v[150:151]
	s_add_i32 m0, s42, 0x2000
	s_nop 0
	global_load_lds_dwordx4 v[224:225], off
	v_lshl_add_u64 v[224:225], v[228:229], 0, s[20:21]
	s_mov_b32 m0, s48
	s_nop 0
	global_load_lds_dwordx4 v[224:225], off
	v_lshl_add_u64 v[224:225], v[230:231], 0, s[20:21]
	s_mov_b32 m0, s49
	s_nop 0
	global_load_lds_dwordx4 v[224:225], off
	s_cmp_lg_u32 s22, 0
	s_cbranch_scc1 .Lgw1_4
	s_waitcnt vmcnt(8)

.Lgw2_4:
	s_barrier
	s_add_i32 s59, s59, 2
	s_add_u32 s38, s38, 0x100
	s_addc_u32 s39, s39, 0
	s_add_u32 s57, s57, 0x100
	s_addc_u32 s58, s58, 0
	s_cmp_gt_u32 s59, 29
	s_cbranch_scc0 .LBB0_975
	s_and_b64 vcc, exec, s[22:23]
	s_cbranch_vccz .LBB0_978
	s_barrier
